# nt hint on f32 residual (hbuf) stores and base loads in the EpiF32 epilogue (cache-retention for bf16 operands)
# baseline (speedup 1.0000x reference)
;     __device__ __forceinline__ void operator()(const Acc& acc, const Unit& u, int wr, int wc, int fr, int fq, const Pre& pre) const {
;         const int row0 = u.pm * 256 + wr * 64 + fr, col0 = u.pn * 256 + wc * 32 + 8 * fq;
;         const size_t zo = (size_t)(u.zb * sOb + u.zh * sOh);
; #pragma unroll
;         for (int ai = 0; ai < 2; ++ai) {
;             f32x4 bv[4][2][2];
;             if (base) {
; #pragma unroll
;                 for (int m = 0; m < 4; ++m) { const size_t off = zo + (size_t)(row0 + ai * 128 + m * 16) * ldc + col0;
; #pragma unroll
;                     for (int bj = 0; bj < 2; ++bj)
; #pragma unroll
;                         for (int n = 0; n < 2; ++n) bv[m][bj][n] = *(const f32x4*)(base + off + bj * 128 + n * 4); }
.Lresync_x_719:
	s_ashr_i32 s0, s42, 31
	s_ashr_i32 s4, s24, 31
	v_readlane_b32 s8, v253, 59
	s_mul_hi_u32 s1, s74, s42
	s_mul_i32 s0, s74, s0
	v_readlane_b32 s9, v253, 60
	s_mul_hi_u32 s5, s8, s24
	s_mul_i32 s4, s8, s4
	s_add_i32 s0, s1, s0
	s_mul_i32 s1, s75, s42
	s_add_i32 s4, s5, s4
	s_mul_i32 s5, s9, s24
	v_lshl_add_u32 v206, s97, 8, v216
	s_add_i32 s0, s0, s1
	s_mul_i32 s1, s74, s42
	s_add_i32 s4, s4, s5
	s_mul_i32 s5, s8, s24
	v_lshl_or_b32 v210, s96, 8, v234
	s_add_u32 s94, s1, s5
	v_ashrrev_i32_e32 v207, 31, v206
	s_addc_u32 s95, s0, s4
	v_ashrrev_i32_e32 v211, 31, v210
	s_mov_b64 s[0:1], -1
	s_and_b64 vcc, exec, s[78:79]
	v_mul_lo_u32 v208, s13, v206
	v_mul_lo_u32 v236, s12, v207
	v_or_b32_e32 v239, 16, v206
	v_or_b32_e32 v238, 32, v206
	v_or_b32_e32 v237, 48, v206
	s_cbranch_vccz .LBB0_722
	s_lshl_b64 s[0:1], s[94:95], 2
	v_readlane_b32 s4, v254, 7
	v_readlane_b32 s5, v254, 8
	s_add_u32 s0, s4, s0
	s_addc_u32 s1, s5, s1
	v_lshl_add_u64 v[154:155], v[210:211], 2, s[0:1]
	v_mad_u64_u32 v[212:213], s[0:1], s12, v206, 0
	v_mul_lo_u32 v124, s13, v239
	v_mad_u64_u32 v[122:123], s[0:1], s12, v239, 0
	v_mul_lo_u32 v140, s13, v238
	v_mad_u64_u32 v[138:139], s[0:1], s12, v238, 0
	v_mul_lo_u32 v158, s13, v237
	v_mad_u64_u32 v[156:157], s[0:1], s12, v237, 0
	v_add3_u32 v213, v213, v236, v208
	v_add3_u32 v123, v123, v236, v124
	v_add3_u32 v139, v139, v236, v140
	v_add3_u32 v157, v157, v236, v158
	v_lshl_add_u64 v[118:119], v[212:213], 2, v[154:155]
	v_lshl_add_u64 v[134:135], v[122:123], 2, v[154:155]
	v_lshl_add_u64 v[150:151], v[138:139], 2, v[154:155]
	v_lshl_add_u64 v[170:171], v[156:157], 2, v[154:155]
	flat_load_dwordx4 v[106:109], v[118:119] nt
	flat_load_dwordx4 v[110:113], v[118:119] offset:16 nt
	flat_load_dwordx4 v[114:117], v[118:119] offset:512 nt
	s_nop 0
	flat_load_dwordx4 v[118:121], v[118:119] offset:528 nt
	s_nop 0
	flat_load_dwordx4 v[122:125], v[134:135] nt
	flat_load_dwordx4 v[126:129], v[134:135] offset:16 nt
	flat_load_dwordx4 v[130:133], v[134:135] offset:512 nt
	s_nop 0
	flat_load_dwordx4 v[134:137], v[134:135] offset:528 nt
	s_nop 0
	flat_load_dwordx4 v[138:141], v[150:151] nt
	flat_load_dwordx4 v[142:145], v[150:151] offset:16 nt
	flat_load_dwordx4 v[146:149], v[150:151] offset:512 nt
	s_nop 0
	flat_load_dwordx4 v[150:153], v[150:151] offset:528 nt
	s_nop 0
	flat_load_dwordx4 v[154:157], v[170:171] nt
	flat_load_dwordx4 v[158:161], v[170:171] offset:16 nt
	flat_load_dwordx4 v[166:169], v[170:171] offset:512 nt
	s_nop 0
	flat_load_dwordx4 v[170:173], v[170:171] offset:528 nt
	s_mov_b64 s[0:1], 0

; __device__ __forceinline__ u32x4 pk8(const f32x4 a, const f32x4 b) { u32x4 w; w.x = pk2(a[0], a[1]); w.y = pk2(a[2], a[3]); w.z = pk2(b[0], b[1]); w.w = pk2(b[2], b[3]); return w; }
;     __device__ __forceinline__ void operator()(const Acc& acc, const Unit& u, int wr, int wc, int fr, int fq, const Pre& pre) const {
;     ...
;             for (int m = 0; m < 4; ++m) { const size_t off = zo + (size_t)(row0 + ai * 128 + m * 16) * ldc + col0; float sq = 0.f;
; #pragma unroll
;                 for (int bj = 0; bj < 2; ++bj) { f32x4 v0 = acc[ai][bj][m][0] * scale, v1 = acc[ai][bj][m][1] * scale;
;                     if (base) { v0 += bv[m][bj][0]; v1 += bv[m][bj][1]; }
;                     *(f32x4*)(O + off + bj * 128) = v0; *(f32x4*)(O + off + bj * 128 + 4) = v1;
;                     if (hb) { *(u32x4*)(hb + off + bj * 128) = pk8(v0, v1);
;                         sq += (v0[0] * v0[0] + v0[1] * v0[1]) + (v0[2] * v0[2] + v0[3] * v0[3]) + (v1[0] * v1[0] + v1[1] * v1[1]) + (v1[2] * v1[2] + v1[3] * v1[3]); } }
;                 if (ssout) { sq += __shfl_xor(sq, 16); sq += __shfl_xor(sq, 32); if (fq == 0) __hip_atomic_fetch_add(ssout + u.zb * zrow + row0 + ai * 128 + m * 16, sq, __ATOMIC_RELAXED, __HIP_MEMORY_SCOPE_AGENT); } }
.LBB0_724:
	v_lshl_add_u64 v[208:209], s[94:95], 0, v[210:211]
	v_lshl_add_u64 v[212:213], v[212:213], 0, v[208:209]
	v_pk_mul_f32 v[214:215], s[80:81], v[192:193]
	v_pk_mul_f32 v[222:223], s[70:71], v[190:191]
	v_pk_mul_f32 v[224:225], s[80:81], v[188:189]
	v_pk_mul_f32 v[226:227], s[70:71], v[186:187]
	s_waitcnt vmcnt(0) lgkmcnt(0)
	v_pk_fma_f32 v[192:193], s[80:81], v[192:193], v[108:109]
	v_pk_fma_f32 v[190:191], s[70:71], v[190:191], v[106:107]
	v_pk_fma_f32 v[228:229], s[80:81], v[188:189], v[112:113]
	v_pk_fma_f32 v[230:231], s[70:71], v[186:187], v[110:111]
	v_cndmask_b32_e64 v194, 0, 1, s[82:83]
	v_cndmask_b32_e64 v189, v193, v215, s[36:37]
	v_cndmask_b32_e64 v188, v192, v214, s[36:37]
	v_cndmask_b32_e64 v187, v191, v223, s[36:37]
	v_cndmask_b32_e64 v186, v190, v222, s[36:37]
	v_cndmask_b32_e64 v193, v229, v225, s[36:37]
	v_cndmask_b32_e64 v192, v228, v224, s[36:37]
	v_cndmask_b32_e64 v191, v231, v227, s[36:37]
	v_cndmask_b32_e64 v190, v230, v226, s[36:37]
	v_lshl_add_u64 v[214:215], v[212:213], 2, s[62:63]
	v_cmp_ne_u32_e64 s[0:1], 1, v194
	s_andn2_b64 vcc, exec, s[82:83]
	v_lshl_add_u64 v[212:213], v[212:213], 1, s[68:69]
	global_store_dwordx4 v[214:215], v[186:189], off nt
	global_store_dwordx4 v[214:215], v[190:193], off offset:16 nt
	s_cbranch_vccnz .LBB0_726
	v_cvt_pk_bf16_f32 v240, v186, v187
	v_cvt_pk_bf16_f32 v241, v188, v189
	v_pk_mul_f32 v[188:189], v[188:189], v[188:189]
	v_pk_mul_f32 v[186:187], v[186:187], v[186:187]
	v_cvt_pk_bf16_f32 v242, v190, v191
	v_pk_mov_b32 v[222:223], v[186:187], v[188:189] op_sel:[1,0]
	v_mov_b32_e32 v187, v189
	v_pk_mul_f32 v[188:189], v[192:193], v[192:193]
	v_pk_mul_f32 v[190:191], v[190:191], v[190:191]
	v_cvt_pk_bf16_f32 v243, v192, v193
	v_pk_add_f32 v[186:187], v[222:223], v[186:187]
	v_mov_b32_e32 v192, v188
	v_mov_b32_e32 v193, v190
	v_mov_b32_e32 v190, v189
	v_pk_add_f32 v[188:189], v[192:193], v[190:191]
	v_add_f32_e32 v186, v186, v187
	v_add_f32_e32 v186, v189, v186
	v_add_f32_e32 v186, v188, v186
	global_store_dwordx4 v[212:213], v[240:243], off
	s_branch .LBB0_727

; __device__ __forceinline__ u32x4 pk8(const f32x4 a, const f32x4 b) { u32x4 w; w.x = pk2(a[0], a[1]); w.y = pk2(a[2], a[3]); w.z = pk2(b[0], b[1]); w.w = pk2(b[2], b[3]); return w; }
;     __device__ __forceinline__ void operator()(const Acc& acc, const Unit& u, int wr, int wc, int fr, int fq, const Pre& pre) const {
;     ...
;             for (int m = 0; m < 4; ++m) { const size_t off = zo + (size_t)(row0 + ai * 128 + m * 16) * ldc + col0; float sq = 0.f;
; #pragma unroll
;                 for (int bj = 0; bj < 2; ++bj) { f32x4 v0 = acc[ai][bj][m][0] * scale, v1 = acc[ai][bj][m][1] * scale;
;                     if (base) { v0 += bv[m][bj][0]; v1 += bv[m][bj][1]; }
;                     *(f32x4*)(O + off + bj * 128) = v0; *(f32x4*)(O + off + bj * 128 + 4) = v1;
;                     if (hb) { *(u32x4*)(hb + off + bj * 128) = pk8(v0, v1);
;                         sq += (v0[0] * v0[0] + v0[1] * v0[1]) + (v0[2] * v0[2] + v0[3] * v0[3]) + (v1[0] * v1[0] + v1[1] * v1[1]) + (v1[2] * v1[2] + v1[3] * v1[3]); } }
;                 if (ssout) { sq += __shfl_xor(sq, 16); sq += __shfl_xor(sq, 32); if (fq == 0) __hip_atomic_fetch_add(ssout + u.zb * zrow + row0 + ai * 128 + m * 16, sq, __ATOMIC_RELAXED, __HIP_MEMORY_SCOPE_AGENT); } }
.LBB0_727:
	v_pk_mul_f32 v[188:189], s[80:81], v[184:185]
	v_pk_mul_f32 v[190:191], s[70:71], v[182:183]
	v_pk_mul_f32 v[192:193], s[80:81], v[180:181]
	v_pk_mul_f32 v[222:223], s[70:71], v[178:179]
	v_pk_fma_f32 v[184:185], s[80:81], v[184:185], v[116:117]
	v_pk_fma_f32 v[182:183], s[70:71], v[182:183], v[114:115]
	v_pk_fma_f32 v[224:225], s[80:81], v[180:181], v[120:121]
	v_pk_fma_f32 v[226:227], s[70:71], v[178:179], v[118:119]
	v_cndmask_b32_e64 v181, v185, v189, s[36:37]
	v_cndmask_b32_e64 v180, v184, v188, s[36:37]
	v_cndmask_b32_e64 v179, v183, v191, s[36:37]
	v_cndmask_b32_e64 v178, v182, v190, s[36:37]
	v_cndmask_b32_e64 v185, v225, v193, s[36:37]
	v_cndmask_b32_e64 v184, v224, v192, s[36:37]
	v_cndmask_b32_e64 v183, v227, v223, s[36:37]
	v_cndmask_b32_e64 v182, v226, v222, s[36:37]
	s_and_b64 vcc, exec, s[0:1]
	global_store_dwordx4 v[214:215], v[178:181], off offset:512 nt
	global_store_dwordx4 v[214:215], v[182:185], off offset:528 nt
	s_cbranch_vccnz .LBB0_729
	v_cvt_pk_bf16_f32 v188, v178, v179
	v_cvt_pk_bf16_f32 v189, v180, v181
	v_cvt_pk_bf16_f32 v190, v182, v183
	v_cvt_pk_bf16_f32 v191, v184, v185
	v_pk_mul_f32 v[180:181], v[180:181], v[180:181]
	v_pk_mul_f32 v[178:179], v[178:179], v[178:179]
	global_store_dwordx4 v[212:213], v[188:191], off offset:256
	v_pk_mul_f32 v[182:183], v[182:183], v[182:183]
	s_nop 0
	v_pk_mov_b32 v[188:189], v[178:179], v[180:181] op_sel:[1,0]
	v_mov_b32_e32 v179, v181
	v_pk_mul_f32 v[180:181], v[184:185], v[184:185]
	v_pk_add_f32 v[178:179], v[188:189], v[178:179]
	v_mov_b32_e32 v184, v180
	v_mov_b32_e32 v185, v182
	v_mov_b32_e32 v182, v181
	v_pk_add_f32 v[180:181], v[184:185], v[182:183]
	v_add_f32_e32 v178, v178, v179
	v_add_f32_e32 v178, v181, v178
	v_add_f32_e32 v178, v180, v178
	v_add_f32_e32 v186, v178, v186

; __device__ __forceinline__ u32x4 pk8(const f32x4 a, const f32x4 b) { u32x4 w; w.x = pk2(a[0], a[1]); w.y = pk2(a[2], a[3]); w.z = pk2(b[0], b[1]); w.w = pk2(b[2], b[3]); return w; }
;     __device__ __forceinline__ void operator()(const Acc& acc, const Unit& u, int wr, int wc, int fr, int fq, const Pre& pre) const {
;     ...
;             for (int m = 0; m < 4; ++m) { const size_t off = zo + (size_t)(row0 + ai * 128 + m * 16) * ldc + col0; float sq = 0.f;
; #pragma unroll
;                 for (int bj = 0; bj < 2; ++bj) { f32x4 v0 = acc[ai][bj][m][0] * scale, v1 = acc[ai][bj][m][1] * scale;
;                     if (base) { v0 += bv[m][bj][0]; v1 += bv[m][bj][1]; }
;                     *(f32x4*)(O + off + bj * 128) = v0; *(f32x4*)(O + off + bj * 128 + 4) = v1;
;                     if (hb) { *(u32x4*)(hb + off + bj * 128) = pk8(v0, v1);
;                         sq += (v0[0] * v0[0] + v0[1] * v0[1]) + (v0[2] * v0[2] + v0[3] * v0[3]) + (v1[0] * v1[0] + v1[1] * v1[1]) + (v1[2] * v1[2] + v1[3] * v1[3]); } }
;                 if (ssout) { sq += __shfl_xor(sq, 16); sq += __shfl_xor(sq, 32); if (fq == 0) __hip_atomic_fetch_add(ssout + u.zb * zrow + row0 + ai * 128 + m * 16, sq, __ATOMIC_RELAXED, __HIP_MEMORY_SCOPE_AGENT); } }
.LBB0_733:
	v_mul_lo_u32 v180, s13, v239
	s_waitcnt lgkmcnt(0)
	v_mad_u64_u32 v[178:179], s[14:15], s12, v239, v[208:209]
	v_add3_u32 v179, v180, v179, v236
	v_pk_mul_f32 v[180:181], s[80:81], v[176:177]
	v_pk_mul_f32 v[182:183], s[70:71], v[174:175]
	v_pk_mul_f32 v[184:185], s[80:81], v[164:165]
	v_pk_mul_f32 v[186:187], s[70:71], v[162:163]
	v_pk_fma_f32 v[176:177], s[80:81], v[176:177], v[124:125]
	v_pk_fma_f32 v[174:175], s[70:71], v[174:175], v[122:123]
	v_pk_fma_f32 v[188:189], s[80:81], v[164:165], v[128:129]
	v_pk_fma_f32 v[190:191], s[70:71], v[162:163], v[126:127]
	v_cndmask_b32_e64 v165, v177, v181, s[36:37]
	v_cndmask_b32_e64 v164, v176, v180, s[36:37]
	v_cndmask_b32_e64 v163, v175, v183, s[36:37]
	v_cndmask_b32_e64 v162, v174, v182, s[36:37]
	v_cndmask_b32_e64 v177, v189, v185, s[36:37]
	v_cndmask_b32_e64 v176, v188, v184, s[36:37]
	v_cndmask_b32_e64 v175, v191, v187, s[36:37]
	v_cndmask_b32_e64 v174, v190, v186, s[36:37]
	v_lshl_add_u64 v[180:181], v[178:179], 2, s[62:63]
	s_and_b64 vcc, exec, s[0:1]
	v_lshl_add_u64 v[178:179], v[178:179], 1, s[68:69]
	global_store_dwordx4 v[180:181], v[162:165], off nt
	global_store_dwordx4 v[180:181], v[174:177], off offset:16 nt
	s_cbranch_vccnz .LBB0_735
	v_cvt_pk_bf16_f32 v182, v162, v163
	v_cvt_pk_bf16_f32 v183, v164, v165
	v_cvt_pk_bf16_f32 v184, v174, v175
	v_cvt_pk_bf16_f32 v185, v176, v177
	v_pk_mul_f32 v[164:165], v[164:165], v[164:165]
	v_pk_mul_f32 v[162:163], v[162:163], v[162:163]
	global_store_dwordx4 v[178:179], v[182:185], off
	v_pk_mul_f32 v[174:175], v[174:175], v[174:175]
	s_nop 0
	v_pk_mov_b32 v[182:183], v[162:163], v[164:165] op_sel:[1,0]
	v_mov_b32_e32 v163, v165
	v_pk_mul_f32 v[164:165], v[176:177], v[176:177]
	v_pk_add_f32 v[162:163], v[182:183], v[162:163]
	v_mov_b32_e32 v176, v164
	v_mov_b32_e32 v177, v174
	v_mov_b32_e32 v174, v165
	v_pk_add_f32 v[164:165], v[176:177], v[174:175]
	v_add_f32_e32 v162, v162, v163
	v_add_f32_e32 v162, v165, v162
	v_add_f32_e32 v162, v164, v162
	s_branch .LBB0_736

; __device__ __forceinline__ u32x4 pk8(const f32x4 a, const f32x4 b) { u32x4 w; w.x = pk2(a[0], a[1]); w.y = pk2(a[2], a[3]); w.z = pk2(b[0], b[1]); w.w = pk2(b[2], b[3]); return w; }
;     __device__ __forceinline__ void operator()(const Acc& acc, const Unit& u, int wr, int wc, int fr, int fq, const Pre& pre) const {
;     ...
;             for (int m = 0; m < 4; ++m) { const size_t off = zo + (size_t)(row0 + ai * 128 + m * 16) * ldc + col0; float sq = 0.f;
; #pragma unroll
;                 for (int bj = 0; bj < 2; ++bj) { f32x4 v0 = acc[ai][bj][m][0] * scale, v1 = acc[ai][bj][m][1] * scale;
;                     if (base) { v0 += bv[m][bj][0]; v1 += bv[m][bj][1]; }
;                     *(f32x4*)(O + off + bj * 128) = v0; *(f32x4*)(O + off + bj * 128 + 4) = v1;
;                     if (hb) { *(u32x4*)(hb + off + bj * 128) = pk8(v0, v1);
;                         sq += (v0[0] * v0[0] + v0[1] * v0[1]) + (v0[2] * v0[2] + v0[3] * v0[3]) + (v1[0] * v1[0] + v1[1] * v1[1]) + (v1[2] * v1[2] + v1[3] * v1[3]); } }
;                 if (ssout) { sq += __shfl_xor(sq, 16); sq += __shfl_xor(sq, 32); if (fq == 0) __hip_atomic_fetch_add(ssout + u.zb * zrow + row0 + ai * 128 + m * 16, sq, __ATOMIC_RELAXED, __HIP_MEMORY_SCOPE_AGENT); } }
.LBB0_736:
	v_pk_mul_f32 v[164:165], s[80:81], v[104:105]
	v_pk_mul_f32 v[174:175], s[70:71], v[102:103]
	v_pk_mul_f32 v[176:177], s[80:81], v[100:101]
	v_pk_mul_f32 v[182:183], s[70:71], v[98:99]
	v_pk_fma_f32 v[104:105], s[80:81], v[104:105], v[132:133]
	v_pk_fma_f32 v[102:103], s[70:71], v[102:103], v[130:131]
	v_pk_fma_f32 v[184:185], s[80:81], v[100:101], v[136:137]
	v_pk_fma_f32 v[186:187], s[70:71], v[98:99], v[134:135]
	v_cndmask_b32_e64 v101, v105, v165, s[36:37]
	v_cndmask_b32_e64 v100, v104, v164, s[36:37]
	v_cndmask_b32_e64 v99, v103, v175, s[36:37]
	v_cndmask_b32_e64 v98, v102, v174, s[36:37]
	v_cndmask_b32_e64 v105, v185, v177, s[36:37]
	v_cndmask_b32_e64 v104, v184, v176, s[36:37]
	v_cndmask_b32_e64 v103, v187, v183, s[36:37]
	v_cndmask_b32_e64 v102, v186, v182, s[36:37]
	s_and_b64 vcc, exec, s[0:1]
	global_store_dwordx4 v[180:181], v[98:101], off offset:512 nt
	global_store_dwordx4 v[180:181], v[102:105], off offset:528 nt
	s_cbranch_vccnz .LBB0_738
	v_cvt_pk_bf16_f32 v174, v98, v99
	v_cvt_pk_bf16_f32 v175, v100, v101
	v_pk_mul_f32 v[100:101], v[100:101], v[100:101]
	v_pk_mul_f32 v[98:99], v[98:99], v[98:99]
	v_cvt_pk_bf16_f32 v176, v102, v103
	v_pk_mov_b32 v[164:165], v[98:99], v[100:101] op_sel:[1,0]
	v_mov_b32_e32 v99, v101
	v_pk_mul_f32 v[100:101], v[104:105], v[104:105]
	v_pk_mul_f32 v[102:103], v[102:103], v[102:103]
	v_cvt_pk_bf16_f32 v177, v104, v105
	v_pk_add_f32 v[98:99], v[164:165], v[98:99]
	v_mov_b32_e32 v104, v100
	v_mov_b32_e32 v105, v102
	v_mov_b32_e32 v102, v101
	v_pk_add_f32 v[100:101], v[104:105], v[102:103]
	v_add_f32_e32 v98, v98, v99
	v_add_f32_e32 v98, v101, v98
	v_add_f32_e32 v98, v100, v98
	v_add_f32_e32 v162, v98, v162
	global_store_dwordx4 v[178:179], v[174:177], off offset:256

; __device__ __forceinline__ u32x4 pk8(const f32x4 a, const f32x4 b) { u32x4 w; w.x = pk2(a[0], a[1]); w.y = pk2(a[2], a[3]); w.z = pk2(b[0], b[1]); w.w = pk2(b[2], b[3]); return w; }
;     __device__ __forceinline__ void operator()(const Acc& acc, const Unit& u, int wr, int wc, int fr, int fq, const Pre& pre) const {
;     ...
;             for (int m = 0; m < 4; ++m) { const size_t off = zo + (size_t)(row0 + ai * 128 + m * 16) * ldc + col0; float sq = 0.f;
; #pragma unroll
;                 for (int bj = 0; bj < 2; ++bj) { f32x4 v0 = acc[ai][bj][m][0] * scale, v1 = acc[ai][bj][m][1] * scale;
;                     if (base) { v0 += bv[m][bj][0]; v1 += bv[m][bj][1]; }
;                     *(f32x4*)(O + off + bj * 128) = v0; *(f32x4*)(O + off + bj * 128 + 4) = v1;
;                     if (hb) { *(u32x4*)(hb + off + bj * 128) = pk8(v0, v1);
;                         sq += (v0[0] * v0[0] + v0[1] * v0[1]) + (v0[2] * v0[2] + v0[3] * v0[3]) + (v1[0] * v1[0] + v1[1] * v1[1]) + (v1[2] * v1[2] + v1[3] * v1[3]); } }
;                 if (ssout) { sq += __shfl_xor(sq, 16); sq += __shfl_xor(sq, 32); if (fq == 0) __hip_atomic_fetch_add(ssout + u.zb * zrow + row0 + ai * 128 + m * 16, sq, __ATOMIC_RELAXED, __HIP_MEMORY_SCOPE_AGENT); } }
.LBB0_742:
	v_mul_lo_u32 v100, s13, v238
	s_waitcnt lgkmcnt(0)
	v_mad_u64_u32 v[98:99], s[14:15], s12, v238, v[208:209]
	v_add3_u32 v99, v100, v99, v236
	v_pk_mul_f32 v[100:101], s[80:81], v[96:97]
	v_pk_mul_f32 v[102:103], s[70:71], v[94:95]
	v_pk_mul_f32 v[104:105], s[80:81], v[92:93]
	v_pk_mul_f32 v[162:163], s[70:71], v[90:91]
	v_pk_fma_f32 v[96:97], s[80:81], v[96:97], v[140:141]
	v_pk_fma_f32 v[94:95], s[70:71], v[94:95], v[138:139]
	v_pk_fma_f32 v[164:165], s[80:81], v[92:93], v[144:145]
	v_pk_fma_f32 v[174:175], s[70:71], v[90:91], v[142:143]
	v_cndmask_b32_e64 v93, v97, v101, s[36:37]
	v_cndmask_b32_e64 v92, v96, v100, s[36:37]
	v_cndmask_b32_e64 v91, v95, v103, s[36:37]
	v_cndmask_b32_e64 v90, v94, v102, s[36:37]
	v_cndmask_b32_e64 v97, v165, v105, s[36:37]
	v_cndmask_b32_e64 v96, v164, v104, s[36:37]
	v_cndmask_b32_e64 v95, v175, v163, s[36:37]
	v_cndmask_b32_e64 v94, v174, v162, s[36:37]
	v_lshl_add_u64 v[100:101], v[98:99], 2, s[62:63]
	s_and_b64 vcc, exec, s[0:1]
	v_lshl_add_u64 v[98:99], v[98:99], 1, s[68:69]
	global_store_dwordx4 v[100:101], v[90:93], off nt
	global_store_dwordx4 v[100:101], v[94:97], off offset:16 nt
	s_cbranch_vccnz .LBB0_744
	v_cvt_pk_bf16_f32 v102, v90, v91
	v_cvt_pk_bf16_f32 v103, v92, v93
	v_cvt_pk_bf16_f32 v104, v94, v95
	v_cvt_pk_bf16_f32 v105, v96, v97
	v_pk_mul_f32 v[92:93], v[92:93], v[92:93]
	v_pk_mul_f32 v[90:91], v[90:91], v[90:91]
	global_store_dwordx4 v[98:99], v[102:105], off
	v_pk_mul_f32 v[94:95], v[94:95], v[94:95]
	s_nop 0
	v_pk_mov_b32 v[102:103], v[90:91], v[92:93] op_sel:[1,0]
	v_mov_b32_e32 v91, v93
	v_pk_mul_f32 v[92:93], v[96:97], v[96:97]
	v_pk_add_f32 v[90:91], v[102:103], v[90:91]
	v_mov_b32_e32 v96, v92
	v_mov_b32_e32 v97, v94
	v_mov_b32_e32 v94, v93
	v_pk_add_f32 v[92:93], v[96:97], v[94:95]
	v_add_f32_e32 v90, v90, v91
	v_add_f32_e32 v90, v93, v90
	v_add_f32_e32 v90, v92, v90
	s_branch .LBB0_745

; __device__ __forceinline__ u32x4 pk8(const f32x4 a, const f32x4 b) { u32x4 w; w.x = pk2(a[0], a[1]); w.y = pk2(a[2], a[3]); w.z = pk2(b[0], b[1]); w.w = pk2(b[2], b[3]); return w; }
;     __device__ __forceinline__ void operator()(const Acc& acc, const Unit& u, int wr, int wc, int fr, int fq, const Pre& pre) const {
;     ...
;             for (int m = 0; m < 4; ++m) { const size_t off = zo + (size_t)(row0 + ai * 128 + m * 16) * ldc + col0; float sq = 0.f;
; #pragma unroll
;                 for (int bj = 0; bj < 2; ++bj) { f32x4 v0 = acc[ai][bj][m][0] * scale, v1 = acc[ai][bj][m][1] * scale;
;                     if (base) { v0 += bv[m][bj][0]; v1 += bv[m][bj][1]; }
;                     *(f32x4*)(O + off + bj * 128) = v0; *(f32x4*)(O + off + bj * 128 + 4) = v1;
;                     if (hb) { *(u32x4*)(hb + off + bj * 128) = pk8(v0, v1);
;                         sq += (v0[0] * v0[0] + v0[1] * v0[1]) + (v0[2] * v0[2] + v0[3] * v0[3]) + (v1[0] * v1[0] + v1[1] * v1[1]) + (v1[2] * v1[2] + v1[3] * v1[3]); } }
;                 if (ssout) { sq += __shfl_xor(sq, 16); sq += __shfl_xor(sq, 32); if (fq == 0) __hip_atomic_fetch_add(ssout + u.zb * zrow + row0 + ai * 128 + m * 16, sq, __ATOMIC_RELAXED, __HIP_MEMORY_SCOPE_AGENT); } }
.LBB0_745:
	v_pk_mul_f32 v[92:93], s[80:81], v[88:89]
	v_pk_mul_f32 v[94:95], s[70:71], v[86:87]
	v_pk_mul_f32 v[96:97], s[80:81], v[84:85]
	v_pk_mul_f32 v[102:103], s[70:71], v[82:83]
	v_pk_fma_f32 v[88:89], s[80:81], v[88:89], v[148:149]
	v_pk_fma_f32 v[86:87], s[70:71], v[86:87], v[146:147]
	v_pk_fma_f32 v[104:105], s[80:81], v[84:85], v[152:153]
	v_pk_fma_f32 v[162:163], s[70:71], v[82:83], v[150:151]
	v_cndmask_b32_e64 v85, v89, v93, s[36:37]
	v_cndmask_b32_e64 v84, v88, v92, s[36:37]
	v_cndmask_b32_e64 v83, v87, v95, s[36:37]
	v_cndmask_b32_e64 v82, v86, v94, s[36:37]
	v_cndmask_b32_e64 v89, v105, v97, s[36:37]
	v_cndmask_b32_e64 v88, v104, v96, s[36:37]
	v_cndmask_b32_e64 v87, v163, v103, s[36:37]
	v_cndmask_b32_e64 v86, v162, v102, s[36:37]
	s_and_b64 vcc, exec, s[0:1]
	global_store_dwordx4 v[100:101], v[82:85], off offset:512 nt
	global_store_dwordx4 v[100:101], v[86:89], off offset:528 nt
	s_cbranch_vccnz .LBB0_747
	v_cvt_pk_bf16_f32 v92, v82, v83
	v_cvt_pk_bf16_f32 v93, v84, v85
	v_cvt_pk_bf16_f32 v94, v86, v87
	v_cvt_pk_bf16_f32 v95, v88, v89
	v_pk_mul_f32 v[84:85], v[84:85], v[84:85]
	v_pk_mul_f32 v[82:83], v[82:83], v[82:83]
	global_store_dwordx4 v[98:99], v[92:95], off offset:256
	v_pk_mul_f32 v[86:87], v[86:87], v[86:87]
	s_nop 0
	v_pk_mov_b32 v[92:93], v[82:83], v[84:85] op_sel:[1,0]
	v_mov_b32_e32 v83, v85
	v_pk_mul_f32 v[84:85], v[88:89], v[88:89]
	v_pk_add_f32 v[82:83], v[92:93], v[82:83]
	v_mov_b32_e32 v88, v84
	v_mov_b32_e32 v89, v86
	v_mov_b32_e32 v86, v85
	v_pk_add_f32 v[84:85], v[88:89], v[86:87]
	v_add_f32_e32 v82, v82, v83
	v_add_f32_e32 v82, v85, v82
	v_add_f32_e32 v82, v84, v82
	v_add_f32_e32 v90, v82, v90

; __device__ __forceinline__ u32x4 pk8(const f32x4 a, const f32x4 b) { u32x4 w; w.x = pk2(a[0], a[1]); w.y = pk2(a[2], a[3]); w.z = pk2(b[0], b[1]); w.w = pk2(b[2], b[3]); return w; }
;     __device__ __forceinline__ void operator()(const Acc& acc, const Unit& u, int wr, int wc, int fr, int fq, const Pre& pre) const {
;     ...
;             for (int m = 0; m < 4; ++m) { const size_t off = zo + (size_t)(row0 + ai * 128 + m * 16) * ldc + col0; float sq = 0.f;
; #pragma unroll
;                 for (int bj = 0; bj < 2; ++bj) { f32x4 v0 = acc[ai][bj][m][0] * scale, v1 = acc[ai][bj][m][1] * scale;
;                     if (base) { v0 += bv[m][bj][0]; v1 += bv[m][bj][1]; }
;                     *(f32x4*)(O + off + bj * 128) = v0; *(f32x4*)(O + off + bj * 128 + 4) = v1;
;                     if (hb) { *(u32x4*)(hb + off + bj * 128) = pk8(v0, v1);
;                         sq += (v0[0] * v0[0] + v0[1] * v0[1]) + (v0[2] * v0[2] + v0[3] * v0[3]) + (v1[0] * v1[0] + v1[1] * v1[1]) + (v1[2] * v1[2] + v1[3] * v1[3]); } }
;                 if (ssout) { sq += __shfl_xor(sq, 16); sq += __shfl_xor(sq, 32); if (fq == 0) __hip_atomic_fetch_add(ssout + u.zb * zrow + row0 + ai * 128 + m * 16, sq, __ATOMIC_RELAXED, __HIP_MEMORY_SCOPE_AGENT); } }
.LBB0_751:
	v_mul_lo_u32 v84, s13, v237
	s_waitcnt lgkmcnt(0)
	v_mad_u64_u32 v[82:83], s[14:15], s12, v237, v[208:209]
	v_add3_u32 v83, v84, v83, v236
	v_pk_mul_f32 v[84:85], s[80:81], v[80:81]
	v_pk_mul_f32 v[86:87], s[70:71], v[78:79]
	v_pk_mul_f32 v[88:89], s[80:81], v[76:77]
	v_pk_mul_f32 v[90:91], s[70:71], v[74:75]
	v_pk_fma_f32 v[80:81], s[80:81], v[80:81], v[156:157]
	v_pk_fma_f32 v[78:79], s[70:71], v[78:79], v[154:155]
	v_pk_fma_f32 v[92:93], s[80:81], v[76:77], v[160:161]
	v_pk_fma_f32 v[94:95], s[70:71], v[74:75], v[158:159]
	v_cndmask_b32_e64 v77, v81, v85, s[36:37]
	v_cndmask_b32_e64 v76, v80, v84, s[36:37]
	v_cndmask_b32_e64 v75, v79, v87, s[36:37]
	v_cndmask_b32_e64 v74, v78, v86, s[36:37]
	v_cndmask_b32_e64 v81, v93, v89, s[36:37]
	v_cndmask_b32_e64 v80, v92, v88, s[36:37]
	v_cndmask_b32_e64 v79, v95, v91, s[36:37]
	v_cndmask_b32_e64 v78, v94, v90, s[36:37]
	v_lshl_add_u64 v[84:85], v[82:83], 2, s[62:63]
	s_and_b64 vcc, exec, s[0:1]
	v_lshl_add_u64 v[82:83], v[82:83], 1, s[68:69]
	global_store_dwordx4 v[84:85], v[74:77], off nt
	global_store_dwordx4 v[84:85], v[78:81], off offset:16 nt
	s_cbranch_vccnz .LBB0_753
	v_cvt_pk_bf16_f32 v86, v74, v75
	v_cvt_pk_bf16_f32 v87, v76, v77
	v_cvt_pk_bf16_f32 v88, v78, v79
	v_cvt_pk_bf16_f32 v89, v80, v81
	v_pk_mul_f32 v[76:77], v[76:77], v[76:77]
	v_pk_mul_f32 v[74:75], v[74:75], v[74:75]
	global_store_dwordx4 v[82:83], v[86:89], off
	v_pk_mul_f32 v[78:79], v[78:79], v[78:79]
	s_nop 0
	v_pk_mov_b32 v[86:87], v[74:75], v[76:77] op_sel:[1,0]
	v_mov_b32_e32 v75, v77
	v_pk_mul_f32 v[76:77], v[80:81], v[80:81]
	v_pk_add_f32 v[74:75], v[86:87], v[74:75]
	v_mov_b32_e32 v80, v76
	v_mov_b32_e32 v81, v78
	v_mov_b32_e32 v78, v77
	v_pk_add_f32 v[76:77], v[80:81], v[78:79]
	v_add_f32_e32 v74, v74, v75
	v_add_f32_e32 v74, v77, v74
	v_add_f32_e32 v74, v76, v74
	s_branch .LBB0_754

; __device__ __forceinline__ u32x4 pk8(const f32x4 a, const f32x4 b) { u32x4 w; w.x = pk2(a[0], a[1]); w.y = pk2(a[2], a[3]); w.z = pk2(b[0], b[1]); w.w = pk2(b[2], b[3]); return w; }
;     __device__ __forceinline__ void operator()(const Acc& acc, const Unit& u, int wr, int wc, int fr, int fq, const Pre& pre) const {
;     ...
;             for (int m = 0; m < 4; ++m) { const size_t off = zo + (size_t)(row0 + ai * 128 + m * 16) * ldc + col0; float sq = 0.f;
; #pragma unroll
;                 for (int bj = 0; bj < 2; ++bj) { f32x4 v0 = acc[ai][bj][m][0] * scale, v1 = acc[ai][bj][m][1] * scale;
;                     if (base) { v0 += bv[m][bj][0]; v1 += bv[m][bj][1]; }
;                     *(f32x4*)(O + off + bj * 128) = v0; *(f32x4*)(O + off + bj * 128 + 4) = v1;
;                     if (hb) { *(u32x4*)(hb + off + bj * 128) = pk8(v0, v1);
;                         sq += (v0[0] * v0[0] + v0[1] * v0[1]) + (v0[2] * v0[2] + v0[3] * v0[3]) + (v1[0] * v1[0] + v1[1] * v1[1]) + (v1[2] * v1[2] + v1[3] * v1[3]); } }
;                 if (ssout) { sq += __shfl_xor(sq, 16); sq += __shfl_xor(sq, 32); if (fq == 0) __hip_atomic_fetch_add(ssout + u.zb * zrow + row0 + ai * 128 + m * 16, sq, __ATOMIC_RELAXED, __HIP_MEMORY_SCOPE_AGENT); } }
.LBB0_754:
	v_pk_mul_f32 v[76:77], s[80:81], v[72:73]
	v_pk_mul_f32 v[78:79], s[70:71], v[70:71]
	v_pk_mul_f32 v[80:81], s[80:81], v[68:69]
	v_pk_mul_f32 v[86:87], s[70:71], v[66:67]
	v_pk_fma_f32 v[72:73], s[80:81], v[72:73], v[168:169]
	v_pk_fma_f32 v[70:71], s[70:71], v[70:71], v[166:167]
	v_pk_fma_f32 v[88:89], s[80:81], v[68:69], v[172:173]
	v_pk_fma_f32 v[90:91], s[70:71], v[66:67], v[170:171]
	v_cndmask_b32_e64 v69, v73, v77, s[36:37]
	v_cndmask_b32_e64 v68, v72, v76, s[36:37]
	v_cndmask_b32_e64 v67, v71, v79, s[36:37]
	v_cndmask_b32_e64 v66, v70, v78, s[36:37]
	v_cndmask_b32_e64 v73, v89, v81, s[36:37]
	v_cndmask_b32_e64 v72, v88, v80, s[36:37]
	v_cndmask_b32_e64 v71, v91, v87, s[36:37]
	v_cndmask_b32_e64 v70, v90, v86, s[36:37]
	s_and_b64 vcc, exec, s[0:1]
	global_store_dwordx4 v[84:85], v[66:69], off offset:512 nt
	global_store_dwordx4 v[84:85], v[70:73], off offset:528 nt
	s_cbranch_vccnz .LBB0_756
	v_cvt_pk_bf16_f32 v76, v66, v67
	v_cvt_pk_bf16_f32 v77, v68, v69
	v_cvt_pk_bf16_f32 v78, v70, v71
	v_cvt_pk_bf16_f32 v79, v72, v73
	v_pk_mul_f32 v[68:69], v[68:69], v[68:69]
	v_pk_mul_f32 v[66:67], v[66:67], v[66:67]
	global_store_dwordx4 v[82:83], v[76:79], off offset:256
	v_pk_mul_f32 v[70:71], v[70:71], v[70:71]
	s_nop 0
	v_pk_mov_b32 v[76:77], v[66:67], v[68:69] op_sel:[1,0]
	v_mov_b32_e32 v67, v69
	v_pk_mul_f32 v[68:69], v[72:73], v[72:73]
	v_pk_add_f32 v[66:67], v[76:77], v[66:67]
	v_mov_b32_e32 v72, v68
	v_mov_b32_e32 v73, v70
	v_mov_b32_e32 v70, v69
	v_pk_add_f32 v[68:69], v[72:73], v[70:71]
	v_add_f32_e32 v66, v66, v67
	v_add_f32_e32 v66, v69, v66
	v_add_f32_e32 v66, v68, v66
	v_add_f32_e32 v74, v66, v74

;     __device__ __forceinline__ void operator()(const Acc& acc, const Unit& u, int wr, int wc, int fr, int fq, const Pre& pre) const {
;     ...
;             if (base) {
; #pragma unroll
;                 for (int m = 0; m < 4; ++m) { const size_t off = zo + (size_t)(row0 + ai * 128 + m * 16) * ldc + col0;
; #pragma unroll
;                     for (int bj = 0; bj < 2; ++bj)
; #pragma unroll
;                         for (int n = 0; n < 2; ++n) bv[m][bj][n] = *(const f32x4*)(base + off + bj * 128 + n * 4); }
.LBB0_760:
	v_add_u32_e32 v237, 0x80, v206
	v_ashrrev_i32_e32 v66, 31, v237
	s_mov_b64 s[96:97], -1
	s_and_b64 vcc, exec, s[78:79]
	v_mul_lo_u32 v238, s13, v237
	v_mul_lo_u32 v239, s12, v66
	v_add_u32_e32 v236, 0x90, v206
	v_add_u32_e32 v215, 0xa0, v206
	v_add_u32_e32 v214, 0xb0, v206
	s_cbranch_vccz .LBB0_762
	s_lshl_b64 s[14:15], s[94:95], 2
	v_readlane_b32 s8, v254, 7
	v_readlane_b32 s9, v254, 8
	s_add_u32 s14, s8, s14
	s_addc_u32 s15, s9, s15
	s_waitcnt lgkmcnt(0)
	v_lshl_add_u64 v[66:67], v[210:211], 2, s[14:15]
	v_mad_u64_u32 v[212:213], s[14:15], s12, v237, 0
	v_add3_u32 v213, v213, v239, v238
	v_lshl_add_u64 v[68:69], v[212:213], 2, v[66:67]
	flat_load_dwordx4 v[190:193], v[68:69] nt
	flat_load_dwordx4 v[186:189], v[68:69] offset:16 nt
	flat_load_dwordx4 v[182:185], v[68:69] offset:512 nt
	flat_load_dwordx4 v[178:181], v[68:69] offset:528 nt
	v_ashrrev_i32_e32 v68, 31, v236
	v_mul_lo_u32 v70, s12, v68
	v_mul_lo_u32 v71, s13, v236
	v_mad_u64_u32 v[68:69], s[14:15], s12, v236, 0
	v_add3_u32 v69, v69, v70, v71
	v_lshl_add_u64 v[68:69], v[68:69], 2, v[66:67]
	flat_load_dwordx4 v[174:177], v[68:69] nt
	flat_load_dwordx4 v[162:165], v[68:69] offset:16 nt
	flat_load_dwordx4 v[102:105], v[68:69] offset:512 nt
	flat_load_dwordx4 v[98:101], v[68:69] offset:528 nt
	v_ashrrev_i32_e32 v68, 31, v215
	v_mul_lo_u32 v70, s12, v68
	v_mul_lo_u32 v71, s13, v215
	v_mad_u64_u32 v[68:69], s[14:15], s12, v215, 0
	v_add3_u32 v69, v69, v70, v71
	v_lshl_add_u64 v[68:69], v[68:69], 2, v[66:67]
	flat_load_dwordx4 v[94:97], v[68:69] nt
	flat_load_dwordx4 v[90:93], v[68:69] offset:16 nt
	flat_load_dwordx4 v[86:89], v[68:69] offset:512 nt
	flat_load_dwordx4 v[82:85], v[68:69] offset:528 nt
	v_ashrrev_i32_e32 v68, 31, v214
	v_mul_lo_u32 v70, s12, v68
	v_mul_lo_u32 v71, s13, v214
	v_mad_u64_u32 v[68:69], s[14:15], s12, v214, 0
	v_add3_u32 v69, v69, v70, v71
	v_lshl_add_u64 v[66:67], v[68:69], 2, v[66:67]
	flat_load_dwordx4 v[78:81], v[66:67] nt
	flat_load_dwordx4 v[74:77], v[66:67] offset:16 nt
	flat_load_dwordx4 v[70:73], v[66:67] offset:512 nt
	s_nop 0
	flat_load_dwordx4 v[66:69], v[66:67] offset:528 nt
	s_mov_b64 s[96:97], 0

; __device__ __forceinline__ u32x4 pk8(const f32x4 a, const f32x4 b) { u32x4 w; w.x = pk2(a[0], a[1]); w.y = pk2(a[2], a[3]); w.z = pk2(b[0], b[1]); w.w = pk2(b[2], b[3]); return w; }
;     __device__ __forceinline__ void operator()(const Acc& acc, const Unit& u, int wr, int wc, int fr, int fq, const Pre& pre) const {
;     ...
;             for (int m = 0; m < 4; ++m) { const size_t off = zo + (size_t)(row0 + ai * 128 + m * 16) * ldc + col0; float sq = 0.f;
; #pragma unroll
;                 for (int bj = 0; bj < 2; ++bj) { f32x4 v0 = acc[ai][bj][m][0] * scale, v1 = acc[ai][bj][m][1] * scale;
;                     if (base) { v0 += bv[m][bj][0]; v1 += bv[m][bj][1]; }
;                     *(f32x4*)(O + off + bj * 128) = v0; *(f32x4*)(O + off + bj * 128 + 4) = v1;
;                     if (hb) { *(u32x4*)(hb + off + bj * 128) = pk8(v0, v1);
;                         sq += (v0[0] * v0[0] + v0[1] * v0[1]) + (v0[2] * v0[2] + v0[3] * v0[3]) + (v1[0] * v1[0] + v1[1] * v1[1]) + (v1[2] * v1[2] + v1[3] * v1[3]); } }
;                 if (ssout) { sq += __shfl_xor(sq, 16); sq += __shfl_xor(sq, 32); if (fq == 0) __hip_atomic_fetch_add(ssout + u.zb * zrow + row0 + ai * 128 + m * 16, sq, __ATOMIC_RELAXED, __HIP_MEMORY_SCOPE_AGENT); } }
.LBB0_764:
	v_lshl_add_u64 v[106:107], v[212:213], 0, v[208:209]
	v_pk_mul_f32 v[108:109], s[80:81], v[64:65]
	v_pk_mul_f32 v[110:111], s[70:71], v[62:63]
	v_pk_mul_f32 v[112:113], s[80:81], v[60:61]
	v_pk_mul_f32 v[114:115], s[70:71], v[58:59]
	s_waitcnt vmcnt(0) lgkmcnt(0)
	v_pk_fma_f32 v[64:65], s[80:81], v[64:65], v[192:193]
	v_pk_fma_f32 v[62:63], s[70:71], v[62:63], v[190:191]
	v_pk_fma_f32 v[116:117], s[80:81], v[60:61], v[188:189]
	v_pk_fma_f32 v[118:119], s[70:71], v[58:59], v[186:187]
	v_cndmask_b32_e64 v61, v65, v109, s[36:37]
	v_cndmask_b32_e64 v60, v64, v108, s[36:37]
	v_cndmask_b32_e64 v59, v63, v111, s[36:37]
	v_cndmask_b32_e64 v58, v62, v110, s[36:37]
	v_cndmask_b32_e64 v65, v117, v113, s[36:37]
	v_cndmask_b32_e64 v64, v116, v112, s[36:37]
	v_cndmask_b32_e64 v63, v119, v115, s[36:37]
	v_cndmask_b32_e64 v62, v118, v114, s[36:37]
	v_lshl_add_u64 v[108:109], v[106:107], 2, s[62:63]
	s_and_b64 vcc, exec, s[0:1]
	v_lshl_add_u64 v[106:107], v[106:107], 1, s[68:69]
	global_store_dwordx4 v[108:109], v[58:61], off nt
	global_store_dwordx4 v[108:109], v[62:65], off offset:16 nt
	s_cbranch_vccnz .LBB0_766
	v_cvt_pk_bf16_f32 v110, v58, v59
	v_cvt_pk_bf16_f32 v111, v60, v61
	v_cvt_pk_bf16_f32 v112, v62, v63
	v_cvt_pk_bf16_f32 v113, v64, v65
	v_pk_mul_f32 v[60:61], v[60:61], v[60:61]
	v_pk_mul_f32 v[58:59], v[58:59], v[58:59]
	global_store_dwordx4 v[106:107], v[110:113], off
	v_pk_mul_f32 v[62:63], v[62:63], v[62:63]
	s_nop 0
	v_pk_mov_b32 v[110:111], v[58:59], v[60:61] op_sel:[1,0]
	v_mov_b32_e32 v59, v61
	v_pk_mul_f32 v[60:61], v[64:65], v[64:65]
	v_pk_add_f32 v[58:59], v[110:111], v[58:59]
	v_mov_b32_e32 v64, v60
	v_mov_b32_e32 v65, v62
	v_mov_b32_e32 v62, v61
	v_pk_add_f32 v[60:61], v[64:65], v[62:63]
	v_add_f32_e32 v58, v58, v59
	v_add_f32_e32 v58, v61, v58
	v_add_f32_e32 v58, v60, v58
	s_branch .LBB0_767

; __device__ __forceinline__ u32x4 pk8(const f32x4 a, const f32x4 b) { u32x4 w; w.x = pk2(a[0], a[1]); w.y = pk2(a[2], a[3]); w.z = pk2(b[0], b[1]); w.w = pk2(b[2], b[3]); return w; }
;     __device__ __forceinline__ void operator()(const Acc& acc, const Unit& u, int wr, int wc, int fr, int fq, const Pre& pre) const {
;     ...
;             for (int m = 0; m < 4; ++m) { const size_t off = zo + (size_t)(row0 + ai * 128 + m * 16) * ldc + col0; float sq = 0.f;
; #pragma unroll
;                 for (int bj = 0; bj < 2; ++bj) { f32x4 v0 = acc[ai][bj][m][0] * scale, v1 = acc[ai][bj][m][1] * scale;
;                     if (base) { v0 += bv[m][bj][0]; v1 += bv[m][bj][1]; }
;                     *(f32x4*)(O + off + bj * 128) = v0; *(f32x4*)(O + off + bj * 128 + 4) = v1;
;                     if (hb) { *(u32x4*)(hb + off + bj * 128) = pk8(v0, v1);
;                         sq += (v0[0] * v0[0] + v0[1] * v0[1]) + (v0[2] * v0[2] + v0[3] * v0[3]) + (v1[0] * v1[0] + v1[1] * v1[1]) + (v1[2] * v1[2] + v1[3] * v1[3]); } }
;                 if (ssout) { sq += __shfl_xor(sq, 16); sq += __shfl_xor(sq, 32); if (fq == 0) __hip_atomic_fetch_add(ssout + u.zb * zrow + row0 + ai * 128 + m * 16, sq, __ATOMIC_RELAXED, __HIP_MEMORY_SCOPE_AGENT); } }
.LBB0_767:
	v_pk_mul_f32 v[60:61], s[80:81], v[56:57]
	v_pk_mul_f32 v[62:63], s[70:71], v[54:55]
	v_pk_mul_f32 v[64:65], s[80:81], v[52:53]
	v_pk_mul_f32 v[110:111], s[70:71], v[50:51]
	v_pk_fma_f32 v[56:57], s[80:81], v[56:57], v[184:185]
	v_pk_fma_f32 v[54:55], s[70:71], v[54:55], v[182:183]
	v_pk_fma_f32 v[112:113], s[80:81], v[52:53], v[180:181]
	v_pk_fma_f32 v[114:115], s[70:71], v[50:51], v[178:179]
	v_cndmask_b32_e64 v53, v57, v61, s[36:37]
	v_cndmask_b32_e64 v52, v56, v60, s[36:37]
	v_cndmask_b32_e64 v51, v55, v63, s[36:37]
	v_cndmask_b32_e64 v50, v54, v62, s[36:37]
	v_cndmask_b32_e64 v57, v113, v65, s[36:37]
	v_cndmask_b32_e64 v56, v112, v64, s[36:37]
	v_cndmask_b32_e64 v55, v115, v111, s[36:37]
	v_cndmask_b32_e64 v54, v114, v110, s[36:37]
	s_and_b64 vcc, exec, s[0:1]
	global_store_dwordx4 v[108:109], v[50:53], off offset:512 nt
	global_store_dwordx4 v[108:109], v[54:57], off offset:528 nt
	s_cbranch_vccnz .LBB0_769
	v_cvt_pk_bf16_f32 v60, v50, v51
	v_cvt_pk_bf16_f32 v61, v52, v53
	v_cvt_pk_bf16_f32 v62, v54, v55
	v_cvt_pk_bf16_f32 v63, v56, v57
	v_pk_mul_f32 v[52:53], v[52:53], v[52:53]
	v_pk_mul_f32 v[50:51], v[50:51], v[50:51]
	global_store_dwordx4 v[106:107], v[60:63], off offset:256
	v_pk_mul_f32 v[54:55], v[54:55], v[54:55]
	s_nop 0
	v_pk_mov_b32 v[60:61], v[50:51], v[52:53] op_sel:[1,0]
	v_mov_b32_e32 v51, v53
	v_pk_mul_f32 v[52:53], v[56:57], v[56:57]
	v_pk_add_f32 v[50:51], v[60:61], v[50:51]
	v_mov_b32_e32 v56, v52
	v_mov_b32_e32 v57, v54
	v_mov_b32_e32 v54, v53
	v_pk_add_f32 v[52:53], v[56:57], v[54:55]
	v_add_f32_e32 v50, v50, v51
	v_add_f32_e32 v50, v53, v50
	v_add_f32_e32 v50, v52, v50
	v_add_f32_e32 v58, v50, v58

; __device__ __forceinline__ u32x4 pk8(const f32x4 a, const f32x4 b) { u32x4 w; w.x = pk2(a[0], a[1]); w.y = pk2(a[2], a[3]); w.z = pk2(b[0], b[1]); w.w = pk2(b[2], b[3]); return w; }
;     __device__ __forceinline__ void operator()(const Acc& acc, const Unit& u, int wr, int wc, int fr, int fq, const Pre& pre) const {
;     ...
;             for (int m = 0; m < 4; ++m) { const size_t off = zo + (size_t)(row0 + ai * 128 + m * 16) * ldc + col0; float sq = 0.f;
; #pragma unroll
;                 for (int bj = 0; bj < 2; ++bj) { f32x4 v0 = acc[ai][bj][m][0] * scale, v1 = acc[ai][bj][m][1] * scale;
;                     if (base) { v0 += bv[m][bj][0]; v1 += bv[m][bj][1]; }
;                     *(f32x4*)(O + off + bj * 128) = v0; *(f32x4*)(O + off + bj * 128 + 4) = v1;
;                     if (hb) { *(u32x4*)(hb + off + bj * 128) = pk8(v0, v1);
;                         sq += (v0[0] * v0[0] + v0[1] * v0[1]) + (v0[2] * v0[2] + v0[3] * v0[3]) + (v1[0] * v1[0] + v1[1] * v1[1]) + (v1[2] * v1[2] + v1[3] * v1[3]); } }
;                 if (ssout) { sq += __shfl_xor(sq, 16); sq += __shfl_xor(sq, 32); if (fq == 0) __hip_atomic_fetch_add(ssout + u.zb * zrow + row0 + ai * 128 + m * 16, sq, __ATOMIC_RELAXED, __HIP_MEMORY_SCOPE_AGENT); } }
.LBB0_773:
	v_ashrrev_i32_e32 v50, 31, v236
	v_mul_lo_u32 v52, s12, v50
	v_mul_lo_u32 v53, s13, v236
	s_waitcnt lgkmcnt(0)
	v_mad_u64_u32 v[50:51], s[14:15], s12, v236, v[208:209]
	v_add3_u32 v51, v53, v51, v52
	v_pk_mul_f32 v[52:53], s[80:81], v[48:49]
	v_pk_mul_f32 v[54:55], s[70:71], v[46:47]
	v_pk_mul_f32 v[56:57], s[80:81], v[44:45]
	v_pk_mul_f32 v[58:59], s[70:71], v[42:43]
	v_pk_fma_f32 v[48:49], s[80:81], v[48:49], v[176:177]
	v_pk_fma_f32 v[46:47], s[70:71], v[46:47], v[174:175]
	v_pk_fma_f32 v[60:61], s[80:81], v[44:45], v[164:165]
	v_pk_fma_f32 v[62:63], s[70:71], v[42:43], v[162:163]
	v_cndmask_b32_e64 v45, v49, v53, s[36:37]
	v_cndmask_b32_e64 v44, v48, v52, s[36:37]
	v_cndmask_b32_e64 v43, v47, v55, s[36:37]
	v_cndmask_b32_e64 v42, v46, v54, s[36:37]
	v_cndmask_b32_e64 v49, v61, v57, s[36:37]
	v_cndmask_b32_e64 v48, v60, v56, s[36:37]
	v_cndmask_b32_e64 v47, v63, v59, s[36:37]
	v_cndmask_b32_e64 v46, v62, v58, s[36:37]
	v_lshl_add_u64 v[52:53], v[50:51], 2, s[62:63]
	s_and_b64 vcc, exec, s[0:1]
	v_lshl_add_u64 v[50:51], v[50:51], 1, s[68:69]
	global_store_dwordx4 v[52:53], v[42:45], off nt
	global_store_dwordx4 v[52:53], v[46:49], off offset:16 nt
	s_cbranch_vccnz .LBB0_775
	v_cvt_pk_bf16_f32 v54, v42, v43
	v_cvt_pk_bf16_f32 v55, v44, v45
	v_cvt_pk_bf16_f32 v56, v46, v47
	v_cvt_pk_bf16_f32 v57, v48, v49
	v_pk_mul_f32 v[44:45], v[44:45], v[44:45]
	v_pk_mul_f32 v[42:43], v[42:43], v[42:43]
	global_store_dwordx4 v[50:51], v[54:57], off
	v_pk_mul_f32 v[46:47], v[46:47], v[46:47]
	s_nop 0
	v_pk_mov_b32 v[54:55], v[42:43], v[44:45] op_sel:[1,0]
	v_mov_b32_e32 v43, v45
	v_pk_mul_f32 v[44:45], v[48:49], v[48:49]
	v_pk_add_f32 v[42:43], v[54:55], v[42:43]
	v_mov_b32_e32 v48, v44
	v_mov_b32_e32 v49, v46
	v_mov_b32_e32 v46, v45
	v_pk_add_f32 v[44:45], v[48:49], v[46:47]
	v_add_f32_e32 v42, v42, v43
	v_add_f32_e32 v42, v45, v42
	v_add_f32_e32 v42, v44, v42
	s_branch .LBB0_776

; __device__ __forceinline__ u32x4 pk8(const f32x4 a, const f32x4 b) { u32x4 w; w.x = pk2(a[0], a[1]); w.y = pk2(a[2], a[3]); w.z = pk2(b[0], b[1]); w.w = pk2(b[2], b[3]); return w; }
;     __device__ __forceinline__ void operator()(const Acc& acc, const Unit& u, int wr, int wc, int fr, int fq, const Pre& pre) const {
;     ...
;             for (int m = 0; m < 4; ++m) { const size_t off = zo + (size_t)(row0 + ai * 128 + m * 16) * ldc + col0; float sq = 0.f;
; #pragma unroll
;                 for (int bj = 0; bj < 2; ++bj) { f32x4 v0 = acc[ai][bj][m][0] * scale, v1 = acc[ai][bj][m][1] * scale;
;                     if (base) { v0 += bv[m][bj][0]; v1 += bv[m][bj][1]; }
;                     *(f32x4*)(O + off + bj * 128) = v0; *(f32x4*)(O + off + bj * 128 + 4) = v1;
;                     if (hb) { *(u32x4*)(hb + off + bj * 128) = pk8(v0, v1);
;                         sq += (v0[0] * v0[0] + v0[1] * v0[1]) + (v0[2] * v0[2] + v0[3] * v0[3]) + (v1[0] * v1[0] + v1[1] * v1[1]) + (v1[2] * v1[2] + v1[3] * v1[3]); } }
;                 if (ssout) { sq += __shfl_xor(sq, 16); sq += __shfl_xor(sq, 32); if (fq == 0) __hip_atomic_fetch_add(ssout + u.zb * zrow + row0 + ai * 128 + m * 16, sq, __ATOMIC_RELAXED, __HIP_MEMORY_SCOPE_AGENT); } }
.LBB0_776:
	v_pk_mul_f32 v[44:45], s[80:81], v[40:41]
	v_pk_mul_f32 v[46:47], s[70:71], v[38:39]
	v_pk_mul_f32 v[48:49], s[80:81], v[36:37]
	v_pk_mul_f32 v[54:55], s[70:71], v[34:35]
	v_pk_fma_f32 v[40:41], s[80:81], v[40:41], v[104:105]
	v_pk_fma_f32 v[38:39], s[70:71], v[38:39], v[102:103]
	v_pk_fma_f32 v[56:57], s[80:81], v[36:37], v[100:101]
	v_pk_fma_f32 v[58:59], s[70:71], v[34:35], v[98:99]
	v_cndmask_b32_e64 v37, v41, v45, s[36:37]
	v_cndmask_b32_e64 v36, v40, v44, s[36:37]
	v_cndmask_b32_e64 v35, v39, v47, s[36:37]
	v_cndmask_b32_e64 v34, v38, v46, s[36:37]
	v_cndmask_b32_e64 v41, v57, v49, s[36:37]
	v_cndmask_b32_e64 v40, v56, v48, s[36:37]
	v_cndmask_b32_e64 v39, v59, v55, s[36:37]
	v_cndmask_b32_e64 v38, v58, v54, s[36:37]
	s_and_b64 vcc, exec, s[0:1]
	global_store_dwordx4 v[52:53], v[34:37], off offset:512 nt
	global_store_dwordx4 v[52:53], v[38:41], off offset:528 nt
	s_cbranch_vccnz .LBB0_778
	v_cvt_pk_bf16_f32 v44, v34, v35
	v_cvt_pk_bf16_f32 v45, v36, v37
	v_cvt_pk_bf16_f32 v46, v38, v39
	v_cvt_pk_bf16_f32 v47, v40, v41
	v_pk_mul_f32 v[36:37], v[36:37], v[36:37]
	v_pk_mul_f32 v[34:35], v[34:35], v[34:35]
	global_store_dwordx4 v[50:51], v[44:47], off offset:256
	v_pk_mul_f32 v[38:39], v[38:39], v[38:39]
	s_nop 0
	v_pk_mov_b32 v[44:45], v[34:35], v[36:37] op_sel:[1,0]
	v_mov_b32_e32 v35, v37
	v_pk_mul_f32 v[36:37], v[40:41], v[40:41]
	v_pk_add_f32 v[34:35], v[44:45], v[34:35]
	v_mov_b32_e32 v40, v36
	v_mov_b32_e32 v41, v38
	v_mov_b32_e32 v38, v37
	v_pk_add_f32 v[36:37], v[40:41], v[38:39]
	v_add_f32_e32 v34, v34, v35
	v_add_f32_e32 v34, v37, v34
	v_add_f32_e32 v34, v36, v34
	v_add_f32_e32 v42, v34, v42

; __device__ __forceinline__ u32x4 pk8(const f32x4 a, const f32x4 b) { u32x4 w; w.x = pk2(a[0], a[1]); w.y = pk2(a[2], a[3]); w.z = pk2(b[0], b[1]); w.w = pk2(b[2], b[3]); return w; }
;     __device__ __forceinline__ void operator()(const Acc& acc, const Unit& u, int wr, int wc, int fr, int fq, const Pre& pre) const {
;     ...
;             for (int m = 0; m < 4; ++m) { const size_t off = zo + (size_t)(row0 + ai * 128 + m * 16) * ldc + col0; float sq = 0.f;
; #pragma unroll
;                 for (int bj = 0; bj < 2; ++bj) { f32x4 v0 = acc[ai][bj][m][0] * scale, v1 = acc[ai][bj][m][1] * scale;
;                     if (base) { v0 += bv[m][bj][0]; v1 += bv[m][bj][1]; }
;                     *(f32x4*)(O + off + bj * 128) = v0; *(f32x4*)(O + off + bj * 128 + 4) = v1;
;                     if (hb) { *(u32x4*)(hb + off + bj * 128) = pk8(v0, v1);
;                         sq += (v0[0] * v0[0] + v0[1] * v0[1]) + (v0[2] * v0[2] + v0[3] * v0[3]) + (v1[0] * v1[0] + v1[1] * v1[1]) + (v1[2] * v1[2] + v1[3] * v1[3]); } }
;                 if (ssout) { sq += __shfl_xor(sq, 16); sq += __shfl_xor(sq, 32); if (fq == 0) __hip_atomic_fetch_add(ssout + u.zb * zrow + row0 + ai * 128 + m * 16, sq, __ATOMIC_RELAXED, __HIP_MEMORY_SCOPE_AGENT); } }
.LBB0_782:
	v_ashrrev_i32_e32 v34, 31, v215
	v_mul_lo_u32 v36, s12, v34
	v_mul_lo_u32 v37, s13, v215
	s_waitcnt lgkmcnt(0)
	v_mad_u64_u32 v[34:35], s[14:15], s12, v215, v[208:209]
	v_add3_u32 v35, v37, v35, v36
	v_pk_mul_f32 v[36:37], s[80:81], v[32:33]
	v_pk_mul_f32 v[38:39], s[70:71], v[30:31]
	v_pk_mul_f32 v[40:41], s[80:81], v[28:29]
	v_pk_mul_f32 v[42:43], s[70:71], v[26:27]
	v_pk_fma_f32 v[32:33], s[80:81], v[32:33], v[96:97]
	v_pk_fma_f32 v[30:31], s[70:71], v[30:31], v[94:95]
	v_pk_fma_f32 v[44:45], s[80:81], v[28:29], v[92:93]
	v_pk_fma_f32 v[46:47], s[70:71], v[26:27], v[90:91]
	v_cndmask_b32_e64 v29, v33, v37, s[36:37]
	v_cndmask_b32_e64 v28, v32, v36, s[36:37]
	v_cndmask_b32_e64 v27, v31, v39, s[36:37]
	v_cndmask_b32_e64 v26, v30, v38, s[36:37]
	v_cndmask_b32_e64 v33, v45, v41, s[36:37]
	v_cndmask_b32_e64 v32, v44, v40, s[36:37]
	v_cndmask_b32_e64 v31, v47, v43, s[36:37]
	v_cndmask_b32_e64 v30, v46, v42, s[36:37]
	v_lshl_add_u64 v[36:37], v[34:35], 2, s[62:63]
	s_and_b64 vcc, exec, s[0:1]
	v_lshl_add_u64 v[34:35], v[34:35], 1, s[68:69]
	global_store_dwordx4 v[36:37], v[26:29], off nt
	global_store_dwordx4 v[36:37], v[30:33], off offset:16 nt
	s_cbranch_vccnz .LBB0_784
	v_cvt_pk_bf16_f32 v38, v26, v27
	v_cvt_pk_bf16_f32 v39, v28, v29
	v_cvt_pk_bf16_f32 v40, v30, v31
	v_cvt_pk_bf16_f32 v41, v32, v33
	v_pk_mul_f32 v[28:29], v[28:29], v[28:29]
	v_pk_mul_f32 v[26:27], v[26:27], v[26:27]
	global_store_dwordx4 v[34:35], v[38:41], off
	v_pk_mul_f32 v[30:31], v[30:31], v[30:31]
	s_nop 0
	v_pk_mov_b32 v[38:39], v[26:27], v[28:29] op_sel:[1,0]
	v_mov_b32_e32 v27, v29
	v_pk_mul_f32 v[28:29], v[32:33], v[32:33]
	v_pk_add_f32 v[26:27], v[38:39], v[26:27]
	v_mov_b32_e32 v32, v28
	v_mov_b32_e32 v33, v30
	v_mov_b32_e32 v30, v29
	v_pk_add_f32 v[28:29], v[32:33], v[30:31]
	v_add_f32_e32 v26, v26, v27
	v_add_f32_e32 v26, v29, v26
	v_add_f32_e32 v26, v28, v26
	s_branch .LBB0_785

; __device__ __forceinline__ u32x4 pk8(const f32x4 a, const f32x4 b) { u32x4 w; w.x = pk2(a[0], a[1]); w.y = pk2(a[2], a[3]); w.z = pk2(b[0], b[1]); w.w = pk2(b[2], b[3]); return w; }
;     __device__ __forceinline__ void operator()(const Acc& acc, const Unit& u, int wr, int wc, int fr, int fq, const Pre& pre) const {
;     ...
;             for (int m = 0; m < 4; ++m) { const size_t off = zo + (size_t)(row0 + ai * 128 + m * 16) * ldc + col0; float sq = 0.f;
; #pragma unroll
;                 for (int bj = 0; bj < 2; ++bj) { f32x4 v0 = acc[ai][bj][m][0] * scale, v1 = acc[ai][bj][m][1] * scale;
;                     if (base) { v0 += bv[m][bj][0]; v1 += bv[m][bj][1]; }
;                     *(f32x4*)(O + off + bj * 128) = v0; *(f32x4*)(O + off + bj * 128 + 4) = v1;
;                     if (hb) { *(u32x4*)(hb + off + bj * 128) = pk8(v0, v1);
;                         sq += (v0[0] * v0[0] + v0[1] * v0[1]) + (v0[2] * v0[2] + v0[3] * v0[3]) + (v1[0] * v1[0] + v1[1] * v1[1]) + (v1[2] * v1[2] + v1[3] * v1[3]); } }
;                 if (ssout) { sq += __shfl_xor(sq, 16); sq += __shfl_xor(sq, 32); if (fq == 0) __hip_atomic_fetch_add(ssout + u.zb * zrow + row0 + ai * 128 + m * 16, sq, __ATOMIC_RELAXED, __HIP_MEMORY_SCOPE_AGENT); } }
.LBB0_785:
	v_pk_mul_f32 v[28:29], s[80:81], v[24:25]
	v_pk_mul_f32 v[30:31], s[70:71], v[22:23]
	v_pk_mul_f32 v[32:33], s[80:81], v[20:21]
	v_pk_mul_f32 v[38:39], s[70:71], v[18:19]
	v_pk_fma_f32 v[24:25], s[80:81], v[24:25], v[88:89]
	v_pk_fma_f32 v[22:23], s[70:71], v[22:23], v[86:87]
	v_pk_fma_f32 v[40:41], s[80:81], v[20:21], v[84:85]
	v_pk_fma_f32 v[42:43], s[70:71], v[18:19], v[82:83]
	v_cndmask_b32_e64 v21, v25, v29, s[36:37]
	v_cndmask_b32_e64 v20, v24, v28, s[36:37]
	v_cndmask_b32_e64 v19, v23, v31, s[36:37]
	v_cndmask_b32_e64 v18, v22, v30, s[36:37]
	v_cndmask_b32_e64 v25, v41, v33, s[36:37]
	v_cndmask_b32_e64 v24, v40, v32, s[36:37]
	v_cndmask_b32_e64 v23, v43, v39, s[36:37]
	v_cndmask_b32_e64 v22, v42, v38, s[36:37]
	s_and_b64 vcc, exec, s[0:1]
	global_store_dwordx4 v[36:37], v[18:21], off offset:512 nt
	global_store_dwordx4 v[36:37], v[22:25], off offset:528 nt
	s_cbranch_vccnz .LBB0_787
	v_cvt_pk_bf16_f32 v28, v18, v19
	v_cvt_pk_bf16_f32 v29, v20, v21
	v_cvt_pk_bf16_f32 v30, v22, v23
	v_cvt_pk_bf16_f32 v31, v24, v25
	v_pk_mul_f32 v[20:21], v[20:21], v[20:21]
	v_pk_mul_f32 v[18:19], v[18:19], v[18:19]
	global_store_dwordx4 v[34:35], v[28:31], off offset:256
	v_pk_mul_f32 v[22:23], v[22:23], v[22:23]
	s_nop 0
	v_pk_mov_b32 v[28:29], v[18:19], v[20:21] op_sel:[1,0]
	v_mov_b32_e32 v19, v21
	v_pk_mul_f32 v[20:21], v[24:25], v[24:25]
	v_pk_add_f32 v[18:19], v[28:29], v[18:19]
	v_mov_b32_e32 v24, v20
	v_mov_b32_e32 v25, v22
	v_mov_b32_e32 v22, v21
	v_pk_add_f32 v[20:21], v[24:25], v[22:23]
	v_add_f32_e32 v18, v18, v19
	v_add_f32_e32 v18, v21, v18
	v_add_f32_e32 v18, v20, v18
	v_add_f32_e32 v26, v18, v26

; __device__ __forceinline__ u32x4 pk8(const f32x4 a, const f32x4 b) { u32x4 w; w.x = pk2(a[0], a[1]); w.y = pk2(a[2], a[3]); w.z = pk2(b[0], b[1]); w.w = pk2(b[2], b[3]); return w; }
;     __device__ __forceinline__ void operator()(const Acc& acc, const Unit& u, int wr, int wc, int fr, int fq, const Pre& pre) const {
;     ...
;             for (int m = 0; m < 4; ++m) { const size_t off = zo + (size_t)(row0 + ai * 128 + m * 16) * ldc + col0; float sq = 0.f;
; #pragma unroll
;                 for (int bj = 0; bj < 2; ++bj) { f32x4 v0 = acc[ai][bj][m][0] * scale, v1 = acc[ai][bj][m][1] * scale;
;                     if (base) { v0 += bv[m][bj][0]; v1 += bv[m][bj][1]; }
;                     *(f32x4*)(O + off + bj * 128) = v0; *(f32x4*)(O + off + bj * 128 + 4) = v1;
;                     if (hb) { *(u32x4*)(hb + off + bj * 128) = pk8(v0, v1);
;                         sq += (v0[0] * v0[0] + v0[1] * v0[1]) + (v0[2] * v0[2] + v0[3] * v0[3]) + (v1[0] * v1[0] + v1[1] * v1[1]) + (v1[2] * v1[2] + v1[3] * v1[3]); } }
;                 if (ssout) { sq += __shfl_xor(sq, 16); sq += __shfl_xor(sq, 32); if (fq == 0) __hip_atomic_fetch_add(ssout + u.zb * zrow + row0 + ai * 128 + m * 16, sq, __ATOMIC_RELAXED, __HIP_MEMORY_SCOPE_AGENT); } }
.LBB0_791:
	v_ashrrev_i32_e32 v18, 31, v214
	v_mul_lo_u32 v20, s12, v18
	v_mul_lo_u32 v21, s13, v214
	s_waitcnt lgkmcnt(0)
	v_mad_u64_u32 v[18:19], s[14:15], s12, v214, v[208:209]
	v_add3_u32 v19, v21, v19, v20
	v_pk_mul_f32 v[20:21], s[80:81], v[16:17]
	v_pk_mul_f32 v[22:23], s[70:71], v[14:15]
	v_pk_mul_f32 v[24:25], s[80:81], v[12:13]
	v_pk_mul_f32 v[26:27], s[70:71], v[10:11]
	v_pk_fma_f32 v[16:17], s[80:81], v[16:17], v[80:81]
	v_pk_fma_f32 v[14:15], s[70:71], v[14:15], v[78:79]
	v_pk_fma_f32 v[28:29], s[80:81], v[12:13], v[76:77]
	v_pk_fma_f32 v[30:31], s[70:71], v[10:11], v[74:75]
	v_cndmask_b32_e64 v13, v17, v21, s[36:37]
	v_cndmask_b32_e64 v12, v16, v20, s[36:37]
	v_cndmask_b32_e64 v11, v15, v23, s[36:37]
	v_cndmask_b32_e64 v10, v14, v22, s[36:37]
	v_cndmask_b32_e64 v17, v29, v25, s[36:37]
	v_cndmask_b32_e64 v16, v28, v24, s[36:37]
	v_cndmask_b32_e64 v15, v31, v27, s[36:37]
	v_cndmask_b32_e64 v14, v30, v26, s[36:37]
	v_lshl_add_u64 v[20:21], v[18:19], 2, s[62:63]
	s_and_b64 vcc, exec, s[0:1]
	v_lshl_add_u64 v[18:19], v[18:19], 1, s[68:69]
	global_store_dwordx4 v[20:21], v[10:13], off nt
	global_store_dwordx4 v[20:21], v[14:17], off offset:16 nt
	s_cbranch_vccnz .LBB0_793
	v_cvt_pk_bf16_f32 v22, v10, v11
	v_cvt_pk_bf16_f32 v23, v12, v13
	v_cvt_pk_bf16_f32 v24, v14, v15
	v_cvt_pk_bf16_f32 v25, v16, v17
	v_pk_mul_f32 v[12:13], v[12:13], v[12:13]
	v_pk_mul_f32 v[10:11], v[10:11], v[10:11]
	global_store_dwordx4 v[18:19], v[22:25], off
	v_pk_mul_f32 v[14:15], v[14:15], v[14:15]
	s_nop 0
	v_pk_mov_b32 v[22:23], v[10:11], v[12:13] op_sel:[1,0]
	v_mov_b32_e32 v11, v13
	v_pk_mul_f32 v[12:13], v[16:17], v[16:17]
	v_pk_add_f32 v[10:11], v[22:23], v[10:11]
	v_mov_b32_e32 v16, v12
	v_mov_b32_e32 v17, v14
	v_mov_b32_e32 v14, v13
	v_pk_add_f32 v[12:13], v[16:17], v[14:15]
	v_add_f32_e32 v10, v10, v11
	v_add_f32_e32 v10, v13, v10
	v_add_f32_e32 v10, v12, v10
	s_branch .LBB0_794

; __device__ __forceinline__ u32x4 pk8(const f32x4 a, const f32x4 b) { u32x4 w; w.x = pk2(a[0], a[1]); w.y = pk2(a[2], a[3]); w.z = pk2(b[0], b[1]); w.w = pk2(b[2], b[3]); return w; }
;     __device__ __forceinline__ void operator()(const Acc& acc, const Unit& u, int wr, int wc, int fr, int fq, const Pre& pre) const {
;     ...
;             for (int m = 0; m < 4; ++m) { const size_t off = zo + (size_t)(row0 + ai * 128 + m * 16) * ldc + col0; float sq = 0.f;
; #pragma unroll
;                 for (int bj = 0; bj < 2; ++bj) { f32x4 v0 = acc[ai][bj][m][0] * scale, v1 = acc[ai][bj][m][1] * scale;
;                     if (base) { v0 += bv[m][bj][0]; v1 += bv[m][bj][1]; }
;                     *(f32x4*)(O + off + bj * 128) = v0; *(f32x4*)(O + off + bj * 128 + 4) = v1;
;                     if (hb) { *(u32x4*)(hb + off + bj * 128) = pk8(v0, v1);
;                         sq += (v0[0] * v0[0] + v0[1] * v0[1]) + (v0[2] * v0[2] + v0[3] * v0[3]) + (v1[0] * v1[0] + v1[1] * v1[1]) + (v1[2] * v1[2] + v1[3] * v1[3]); } }
;                 if (ssout) { sq += __shfl_xor(sq, 16); sq += __shfl_xor(sq, 32); if (fq == 0) __hip_atomic_fetch_add(ssout + u.zb * zrow + row0 + ai * 128 + m * 16, sq, __ATOMIC_RELAXED, __HIP_MEMORY_SCOPE_AGENT); } }
.LBB0_794:
	v_pk_mul_f32 v[12:13], s[80:81], v[8:9]
	v_pk_mul_f32 v[14:15], s[70:71], v[6:7]
	v_pk_mul_f32 v[16:17], s[80:81], v[4:5]
	v_pk_mul_f32 v[22:23], s[70:71], v[2:3]
	v_pk_fma_f32 v[8:9], s[80:81], v[8:9], v[72:73]
	v_pk_fma_f32 v[6:7], s[70:71], v[6:7], v[70:71]
	v_pk_fma_f32 v[24:25], s[80:81], v[4:5], v[68:69]
	v_pk_fma_f32 v[26:27], s[70:71], v[2:3], v[66:67]
	v_cndmask_b32_e64 v5, v9, v13, s[36:37]
	v_cndmask_b32_e64 v4, v8, v12, s[36:37]
	v_cndmask_b32_e64 v3, v7, v15, s[36:37]
	v_cndmask_b32_e64 v2, v6, v14, s[36:37]
	v_cndmask_b32_e64 v9, v25, v17, s[36:37]
	v_cndmask_b32_e64 v8, v24, v16, s[36:37]
	v_cndmask_b32_e64 v7, v27, v23, s[36:37]
	v_cndmask_b32_e64 v6, v26, v22, s[36:37]
	s_and_b64 vcc, exec, s[0:1]
	global_store_dwordx4 v[20:21], v[2:5], off offset:512 nt
	global_store_dwordx4 v[20:21], v[6:9], off offset:528 nt
	s_cbranch_vccnz .LBB0_796
	v_cvt_pk_bf16_f32 v12, v2, v3
	v_cvt_pk_bf16_f32 v13, v4, v5
	v_cvt_pk_bf16_f32 v14, v6, v7
	v_cvt_pk_bf16_f32 v15, v8, v9
	v_pk_mul_f32 v[4:5], v[4:5], v[4:5]
	v_pk_mul_f32 v[2:3], v[2:3], v[2:3]
	global_store_dwordx4 v[18:19], v[12:15], off offset:256
	v_pk_mul_f32 v[6:7], v[6:7], v[6:7]
	s_nop 0
	v_pk_mov_b32 v[12:13], v[2:3], v[4:5] op_sel:[1,0]
	v_mov_b32_e32 v3, v5
	v_pk_mul_f32 v[4:5], v[8:9], v[8:9]
	v_pk_add_f32 v[2:3], v[12:13], v[2:3]
	v_mov_b32_e32 v8, v4
	v_mov_b32_e32 v9, v6
	v_mov_b32_e32 v6, v5
	v_pk_add_f32 v[4:5], v[8:9], v[6:7]
	v_add_f32_e32 v2, v2, v3
	v_add_f32_e32 v2, v5, v2
	v_add_f32_e32 v2, v4, v2
	v_add_f32_e32 v10, v2, v10
